# phase_mod GEMV loop software-pipelined: each weight row of the next iteration is re-loaded right after the FMAs that consumed it (addresses in dead VGPRs), counted vmcnt(7) waits
# baseline (speedup 1.0000x reference)
.LBB0_13:
	v_add_co_u32_e64 v216, s[6:7], s26, v42
	s_nop 1
	v_addc_co_u32_e64 v217, s[6:7], -1, v43, s[6:7]
	v_add_co_u32_e64 v218, s[6:7], s27, v42
	s_nop 1
	v_addc_co_u32_e64 v219, s[6:7], -1, v43, s[6:7]
	v_add_co_u32_e64 v220, s[6:7], s28, v42
	s_nop 1
	v_addc_co_u32_e64 v221, s[6:7], -1, v43, s[6:7]
	v_add_co_u32_e64 v222, s[6:7], s29, v42
	s_nop 1
	v_addc_co_u32_e64 v223, s[6:7], -1, v43, s[6:7]
	v_add_co_u32_e64 v224, s[6:7], s31, v42
	s_nop 1
	v_addc_co_u32_e64 v225, s[6:7], 0, v43, s[6:7]
	v_add_co_u32_e64 v226, s[6:7], s25, v42
	s_nop 1
	v_addc_co_u32_e64 v227, s[6:7], 0, v43, s[6:7]
	v_add_co_u32_e64 v228, s[6:7], s30, v42
	s_nop 1
	v_addc_co_u32_e64 v229, s[6:7], 0, v43, s[6:7]
	s_nop 1
	global_load_dwordx4 v[50:53], v[216:217], off
	global_load_dwordx4 v[54:57], v[218:219], off
	global_load_dwordx4 v[44:47], v[220:221], off
	global_load_dwordx4 v[122:125], v[222:223], off
	global_load_dwordx4 v[130:133], v[42:43], off
	global_load_dwordx4 v[134:137], v[226:227], off
	global_load_dwordx4 v[138:141], v[228:229], off
	global_load_dwordx4 v[126:129], v[224:225], off
.Lpm_loop:
	v_add_u32_e32 v232, s17, v1
	s_add_i32 s17, s17, 32
	ds_read_b128 v[58:61], v232
	ds_read_b128 v[62:65], v232 offset:16
	ds_read_b128 v[66:69], v232 offset:8192
	ds_read_b128 v[70:73], v232 offset:8208
	ds_read_b128 v[74:77], v232 offset:16384
	ds_read_b128 v[78:81], v232 offset:16400
	ds_read_b128 v[82:85], v232 offset:24576
	ds_read_b128 v[86:89], v232 offset:24592
	ds_read_b128 v[90:93], v232 offset:32768
	ds_read_b128 v[94:97], v232 offset:32784
	ds_read_b128 v[98:101], v232 offset:40960
	ds_read_b128 v[102:105], v232 offset:40976
	ds_read_b128 v[106:109], v232 offset:49152
	ds_read_b128 v[110:113], v232 offset:49168
	ds_read_b128 v[114:117], v232 offset:57344
	ds_read_b128 v[118:121], v232 offset:57360
	v_add_u32_e32 v48, 0x10000, v232
	v_add_u32_e32 v49, 0x10010, v232
	ds_read_b128 v[142:145], v48
	ds_read_b128 v[146:149], v49
	s_waitcnt lgkmcnt(14)
	v_mov_b32_e32 v48, v61
	v_mov_b32_e32 v150, v69
	s_waitcnt lgkmcnt(13)
	v_mov_b32_e32 v152, v77
	s_waitcnt lgkmcnt(11)
	v_mov_b32_e32 v154, v85
	s_waitcnt lgkmcnt(9)
	v_mov_b32_e32 v156, v93
	s_waitcnt lgkmcnt(7)
	v_mov_b32_e32 v158, v101
	s_waitcnt lgkmcnt(5)
	v_mov_b32_e32 v160, v109
	s_waitcnt lgkmcnt(3)
	v_mov_b32_e32 v162, v117
	s_waitcnt lgkmcnt(1)
	v_mov_b32_e32 v180, v145
	v_mov_b32_e32 v164, v65
	v_mov_b32_e32 v166, v73
	v_mov_b32_e32 v168, v81
	v_mov_b32_e32 v170, v89
	v_mov_b32_e32 v172, v97
	v_mov_b32_e32 v174, v105
	v_mov_b32_e32 v176, v113
	v_mov_b32_e32 v178, v121
	s_waitcnt lgkmcnt(0)
	v_mov_b32_e32 v182, v149
	v_lshl_add_u64 v[42:43], v[42:43], 0, s[12:13]
	v_add_co_u32_e64 v216, s[6:7], s26, v42
	s_nop 1
	v_addc_co_u32_e64 v217, s[6:7], -1, v43, s[6:7]
	v_add_co_u32_e64 v218, s[6:7], s27, v42
	s_nop 1
	v_addc_co_u32_e64 v219, s[6:7], -1, v43, s[6:7]
	v_add_co_u32_e64 v220, s[6:7], s28, v42
	s_nop 1
	v_addc_co_u32_e64 v221, s[6:7], -1, v43, s[6:7]
	v_add_co_u32_e64 v222, s[6:7], s29, v42
	s_nop 1
	v_addc_co_u32_e64 v223, s[6:7], -1, v43, s[6:7]
	v_add_co_u32_e64 v224, s[6:7], s31, v42
	s_nop 1
	v_addc_co_u32_e64 v225, s[6:7], 0, v43, s[6:7]
	v_add_co_u32_e64 v226, s[6:7], s25, v42
	s_nop 1
	v_addc_co_u32_e64 v227, s[6:7], 0, v43, s[6:7]
	v_add_co_u32_e64 v228, s[6:7], s30, v42
	s_nop 1
	v_addc_co_u32_e64 v229, s[6:7], 0, v43, s[6:7]
	s_waitcnt vmcnt(7)
	v_pk_fma_f32 v[22:23], v[58:59], v[50:51], v[22:23] op_sel_hi:[0,1,1]
	v_pk_fma_f32 v[24:25], v[58:59], v[52:53], v[24:25] op_sel_hi:[0,1,1]
	v_pk_fma_f32 v[34:35], v[50:51], v[66:67], v[34:35] op_sel_hi:[1,0,1]
	v_pk_fma_f32 v[36:37], v[52:53], v[66:67], v[36:37] op_sel_hi:[1,0,1]
	v_pk_fma_f32 v[30:31], v[50:51], v[74:75], v[30:31] op_sel_hi:[1,0,1]
	v_pk_fma_f32 v[32:33], v[52:53], v[74:75], v[32:33] op_sel_hi:[1,0,1]
	v_pk_fma_f32 v[26:27], v[50:51], v[82:83], v[26:27] op_sel_hi:[1,0,1]
	v_pk_fma_f32 v[28:29], v[52:53], v[82:83], v[28:29] op_sel_hi:[1,0,1]
	v_pk_fma_f32 v[18:19], v[50:51], v[90:91], v[18:19] op_sel_hi:[1,0,1]
	v_pk_fma_f32 v[20:21], v[52:53], v[90:91], v[20:21] op_sel_hi:[1,0,1]
	v_pk_fma_f32 v[14:15], v[50:51], v[98:99], v[14:15] op_sel_hi:[1,0,1]
	v_pk_fma_f32 v[16:17], v[52:53], v[98:99], v[16:17] op_sel_hi:[1,0,1]
	v_pk_fma_f32 v[10:11], v[50:51], v[106:107], v[10:11] op_sel_hi:[1,0,1]
	v_pk_fma_f32 v[12:13], v[52:53], v[106:107], v[12:13] op_sel_hi:[1,0,1]
	v_pk_fma_f32 v[6:7], v[50:51], v[114:115], v[6:7] op_sel_hi:[1,0,1]
	v_pk_fma_f32 v[8:9], v[52:53], v[114:115], v[8:9] op_sel_hi:[1,0,1]
	v_pk_fma_f32 v[2:3], v[50:51], v[142:143], v[2:3] op_sel_hi:[1,0,1]
	v_pk_fma_f32 v[4:5], v[52:53], v[142:143], v[4:5] op_sel_hi:[1,0,1]
	global_load_dwordx4 v[50:53], v[216:217], off
	s_waitcnt vmcnt(7)
	v_pk_fma_f32 v[22:23], v[58:59], v[54:55], v[22:23] op_sel:[1,0,0]
	v_pk_fma_f32 v[24:25], v[58:59], v[56:57], v[24:25] op_sel:[1,0,0]
	v_pk_fma_f32 v[34:35], v[54:55], v[66:67], v[34:35] op_sel:[0,1,0]
	v_pk_fma_f32 v[36:37], v[56:57], v[66:67], v[36:37] op_sel:[0,1,0]
	v_pk_fma_f32 v[30:31], v[54:55], v[74:75], v[30:31] op_sel:[0,1,0]
	v_pk_fma_f32 v[32:33], v[56:57], v[74:75], v[32:33] op_sel:[0,1,0]
	v_pk_fma_f32 v[26:27], v[54:55], v[82:83], v[26:27] op_sel:[0,1,0]
	v_pk_fma_f32 v[28:29], v[56:57], v[82:83], v[28:29] op_sel:[0,1,0]
	v_pk_fma_f32 v[18:19], v[54:55], v[90:91], v[18:19] op_sel:[0,1,0]
	v_pk_fma_f32 v[20:21], v[56:57], v[90:91], v[20:21] op_sel:[0,1,0]
	v_pk_fma_f32 v[14:15], v[54:55], v[98:99], v[14:15] op_sel:[0,1,0]
	v_pk_fma_f32 v[16:17], v[56:57], v[98:99], v[16:17] op_sel:[0,1,0]
	v_pk_fma_f32 v[10:11], v[54:55], v[106:107], v[10:11] op_sel:[0,1,0]
	v_pk_fma_f32 v[12:13], v[56:57], v[106:107], v[12:13] op_sel:[0,1,0]
	v_pk_fma_f32 v[6:7], v[54:55], v[114:115], v[6:7] op_sel:[0,1,0]
	v_pk_fma_f32 v[8:9], v[56:57], v[114:115], v[8:9] op_sel:[0,1,0]
	v_pk_fma_f32 v[2:3], v[54:55], v[142:143], v[2:3] op_sel:[0,1,0]
	v_pk_fma_f32 v[4:5], v[56:57], v[142:143], v[4:5] op_sel:[0,1,0]
	global_load_dwordx4 v[54:57], v[218:219], off
	s_waitcnt vmcnt(7)
	v_pk_fma_f32 v[22:23], v[60:61], v[44:45], v[22:23] op_sel_hi:[0,1,1]
	v_pk_fma_f32 v[24:25], v[60:61], v[46:47], v[24:25] op_sel_hi:[0,1,1]
	v_pk_fma_f32 v[34:35], v[44:45], v[68:69], v[34:35] op_sel_hi:[1,0,1]
	v_pk_fma_f32 v[36:37], v[46:47], v[68:69], v[36:37] op_sel_hi:[1,0,1]
	v_pk_fma_f32 v[30:31], v[44:45], v[76:77], v[30:31] op_sel_hi:[1,0,1]
	v_pk_fma_f32 v[32:33], v[46:47], v[76:77], v[32:33] op_sel_hi:[1,0,1]
	v_pk_fma_f32 v[26:27], v[44:45], v[84:85], v[26:27] op_sel_hi:[1,0,1]
	v_pk_fma_f32 v[28:29], v[46:47], v[84:85], v[28:29] op_sel_hi:[1,0,1]
	v_pk_fma_f32 v[18:19], v[44:45], v[92:93], v[18:19] op_sel_hi:[1,0,1]
	v_pk_fma_f32 v[20:21], v[46:47], v[92:93], v[20:21] op_sel_hi:[1,0,1]
	v_pk_fma_f32 v[14:15], v[44:45], v[100:101], v[14:15] op_sel_hi:[1,0,1]
	v_pk_fma_f32 v[16:17], v[46:47], v[100:101], v[16:17] op_sel_hi:[1,0,1]
	v_pk_fma_f32 v[10:11], v[44:45], v[108:109], v[10:11] op_sel_hi:[1,0,1]
	v_pk_fma_f32 v[12:13], v[46:47], v[108:109], v[12:13] op_sel_hi:[1,0,1]
	v_pk_fma_f32 v[6:7], v[44:45], v[116:117], v[6:7] op_sel_hi:[1,0,1]
	v_pk_fma_f32 v[8:9], v[46:47], v[116:117], v[8:9] op_sel_hi:[1,0,1]
	v_pk_fma_f32 v[2:3], v[44:45], v[144:145], v[2:3] op_sel_hi:[1,0,1]
	v_pk_fma_f32 v[4:5], v[46:47], v[144:145], v[4:5] op_sel_hi:[1,0,1]
	global_load_dwordx4 v[44:47], v[220:221], off
	s_waitcnt vmcnt(7)
	v_pk_fma_f32 v[22:23], v[48:49], v[122:123], v[22:23] op_sel_hi:[0,1,1]
	v_pk_fma_f32 v[24:25], v[48:49], v[124:125], v[24:25] op_sel_hi:[0,1,1]
	v_pk_fma_f32 v[34:35], v[122:123], v[150:151], v[34:35] op_sel_hi:[1,0,1]
	v_pk_fma_f32 v[36:37], v[124:125], v[150:151], v[36:37] op_sel_hi:[1,0,1]
	v_pk_fma_f32 v[30:31], v[122:123], v[152:153], v[30:31] op_sel_hi:[1,0,1]
	v_pk_fma_f32 v[32:33], v[124:125], v[152:153], v[32:33] op_sel_hi:[1,0,1]
	v_pk_fma_f32 v[26:27], v[122:123], v[154:155], v[26:27] op_sel_hi:[1,0,1]
	v_pk_fma_f32 v[28:29], v[124:125], v[154:155], v[28:29] op_sel_hi:[1,0,1]
	v_pk_fma_f32 v[18:19], v[122:123], v[156:157], v[18:19] op_sel_hi:[1,0,1]
	v_pk_fma_f32 v[20:21], v[124:125], v[156:157], v[20:21] op_sel_hi:[1,0,1]
	v_pk_fma_f32 v[14:15], v[122:123], v[158:159], v[14:15] op_sel_hi:[1,0,1]
	v_pk_fma_f32 v[16:17], v[124:125], v[158:159], v[16:17] op_sel_hi:[1,0,1]
	v_pk_fma_f32 v[10:11], v[122:123], v[160:161], v[10:11] op_sel_hi:[1,0,1]
	v_pk_fma_f32 v[12:13], v[124:125], v[160:161], v[12:13] op_sel_hi:[1,0,1]
	v_pk_fma_f32 v[6:7], v[122:123], v[162:163], v[6:7] op_sel_hi:[1,0,1]
	v_pk_fma_f32 v[8:9], v[124:125], v[162:163], v[8:9] op_sel_hi:[1,0,1]
	v_pk_fma_f32 v[2:3], v[122:123], v[180:181], v[2:3] op_sel_hi:[1,0,1]
	v_pk_fma_f32 v[4:5], v[124:125], v[180:181], v[4:5] op_sel_hi:[1,0,1]
	global_load_dwordx4 v[122:125], v[222:223], off
	s_waitcnt vmcnt(7)
	v_pk_fma_f32 v[22:23], v[62:63], v[130:131], v[22:23] op_sel_hi:[0,1,1]
	v_pk_fma_f32 v[24:25], v[62:63], v[132:133], v[24:25] op_sel_hi:[0,1,1]
	v_pk_fma_f32 v[34:35], v[130:131], v[70:71], v[34:35] op_sel_hi:[1,0,1]
	v_pk_fma_f32 v[36:37], v[132:133], v[70:71], v[36:37] op_sel_hi:[1,0,1]
	v_pk_fma_f32 v[30:31], v[130:131], v[78:79], v[30:31] op_sel_hi:[1,0,1]
	v_pk_fma_f32 v[32:33], v[132:133], v[78:79], v[32:33] op_sel_hi:[1,0,1]
	v_pk_fma_f32 v[26:27], v[130:131], v[86:87], v[26:27] op_sel_hi:[1,0,1]
	v_pk_fma_f32 v[28:29], v[132:133], v[86:87], v[28:29] op_sel_hi:[1,0,1]
	v_pk_fma_f32 v[18:19], v[130:131], v[94:95], v[18:19] op_sel_hi:[1,0,1]
	v_pk_fma_f32 v[20:21], v[132:133], v[94:95], v[20:21] op_sel_hi:[1,0,1]
	v_pk_fma_f32 v[14:15], v[130:131], v[102:103], v[14:15] op_sel_hi:[1,0,1]
	v_pk_fma_f32 v[16:17], v[132:133], v[102:103], v[16:17] op_sel_hi:[1,0,1]
	v_pk_fma_f32 v[10:11], v[130:131], v[110:111], v[10:11] op_sel_hi:[1,0,1]
	v_pk_fma_f32 v[12:13], v[132:133], v[110:111], v[12:13] op_sel_hi:[1,0,1]
	v_pk_fma_f32 v[6:7], v[130:131], v[118:119], v[6:7] op_sel_hi:[1,0,1]
	v_pk_fma_f32 v[8:9], v[132:133], v[118:119], v[8:9] op_sel_hi:[1,0,1]
	v_pk_fma_f32 v[2:3], v[130:131], v[146:147], v[2:3] op_sel_hi:[1,0,1]
	v_pk_fma_f32 v[4:5], v[132:133], v[146:147], v[4:5] op_sel_hi:[1,0,1]
	global_load_dwordx4 v[130:133], v[42:43], off
	s_waitcnt vmcnt(7)
	v_pk_fma_f32 v[22:23], v[62:63], v[134:135], v[22:23] op_sel:[1,0,0]
	v_pk_fma_f32 v[24:25], v[62:63], v[136:137], v[24:25] op_sel:[1,0,0]
	v_pk_fma_f32 v[34:35], v[134:135], v[70:71], v[34:35] op_sel:[0,1,0]
	v_pk_fma_f32 v[36:37], v[136:137], v[70:71], v[36:37] op_sel:[0,1,0]
	v_pk_fma_f32 v[30:31], v[134:135], v[78:79], v[30:31] op_sel:[0,1,0]
	v_pk_fma_f32 v[32:33], v[136:137], v[78:79], v[32:33] op_sel:[0,1,0]
	v_pk_fma_f32 v[26:27], v[134:135], v[86:87], v[26:27] op_sel:[0,1,0]
	v_pk_fma_f32 v[28:29], v[136:137], v[86:87], v[28:29] op_sel:[0,1,0]
	v_pk_fma_f32 v[18:19], v[134:135], v[94:95], v[18:19] op_sel:[0,1,0]
	v_pk_fma_f32 v[20:21], v[136:137], v[94:95], v[20:21] op_sel:[0,1,0]
	v_pk_fma_f32 v[14:15], v[134:135], v[102:103], v[14:15] op_sel:[0,1,0]
	v_pk_fma_f32 v[16:17], v[136:137], v[102:103], v[16:17] op_sel:[0,1,0]
	v_pk_fma_f32 v[10:11], v[134:135], v[110:111], v[10:11] op_sel:[0,1,0]
	v_pk_fma_f32 v[12:13], v[136:137], v[110:111], v[12:13] op_sel:[0,1,0]
	v_pk_fma_f32 v[6:7], v[134:135], v[118:119], v[6:7] op_sel:[0,1,0]
	v_pk_fma_f32 v[8:9], v[136:137], v[118:119], v[8:9] op_sel:[0,1,0]
	v_pk_fma_f32 v[2:3], v[134:135], v[146:147], v[2:3] op_sel:[0,1,0]
	v_pk_fma_f32 v[4:5], v[136:137], v[146:147], v[4:5] op_sel:[0,1,0]
	global_load_dwordx4 v[134:137], v[226:227], off
	s_waitcnt vmcnt(6)
	v_pk_fma_f32 v[22:23], v[64:65], v[138:139], v[22:23] op_sel_hi:[0,1,1]
	v_pk_fma_f32 v[24:25], v[64:65], v[140:141], v[24:25] op_sel_hi:[0,1,1]
	v_pk_fma_f32 v[34:35], v[138:139], v[72:73], v[34:35] op_sel_hi:[1,0,1]
	v_pk_fma_f32 v[36:37], v[140:141], v[72:73], v[36:37] op_sel_hi:[1,0,1]
	v_pk_fma_f32 v[30:31], v[138:139], v[80:81], v[30:31] op_sel_hi:[1,0,1]
	v_pk_fma_f32 v[32:33], v[140:141], v[80:81], v[32:33] op_sel_hi:[1,0,1]
	v_pk_fma_f32 v[26:27], v[138:139], v[88:89], v[26:27] op_sel_hi:[1,0,1]
	v_pk_fma_f32 v[28:29], v[140:141], v[88:89], v[28:29] op_sel_hi:[1,0,1]
	v_pk_fma_f32 v[18:19], v[138:139], v[96:97], v[18:19] op_sel_hi:[1,0,1]
	v_pk_fma_f32 v[20:21], v[140:141], v[96:97], v[20:21] op_sel_hi:[1,0,1]
	v_pk_fma_f32 v[14:15], v[138:139], v[104:105], v[14:15] op_sel_hi:[1,0,1]
	v_pk_fma_f32 v[16:17], v[140:141], v[104:105], v[16:17] op_sel_hi:[1,0,1]
	v_pk_fma_f32 v[10:11], v[138:139], v[112:113], v[10:11] op_sel_hi:[1,0,1]
	v_pk_fma_f32 v[12:13], v[140:141], v[112:113], v[12:13] op_sel_hi:[1,0,1]
	v_pk_fma_f32 v[6:7], v[138:139], v[120:121], v[6:7] op_sel_hi:[1,0,1]
	v_pk_fma_f32 v[8:9], v[140:141], v[120:121], v[8:9] op_sel_hi:[1,0,1]
	v_pk_fma_f32 v[2:3], v[138:139], v[148:149], v[2:3] op_sel_hi:[1,0,1]
	v_pk_fma_f32 v[4:5], v[140:141], v[148:149], v[4:5] op_sel_hi:[1,0,1]
	v_pk_fma_f32 v[22:23], v[164:165], v[126:127], v[22:23] op_sel_hi:[0,1,1]
	v_pk_fma_f32 v[24:25], v[164:165], v[128:129], v[24:25] op_sel_hi:[0,1,1]
	v_pk_fma_f32 v[34:35], v[126:127], v[166:167], v[34:35] op_sel_hi:[1,0,1]
	v_pk_fma_f32 v[36:37], v[128:129], v[166:167], v[36:37] op_sel_hi:[1,0,1]
	v_pk_fma_f32 v[30:31], v[126:127], v[168:169], v[30:31] op_sel_hi:[1,0,1]
	v_pk_fma_f32 v[32:33], v[128:129], v[168:169], v[32:33] op_sel_hi:[1,0,1]
	v_pk_fma_f32 v[26:27], v[126:127], v[170:171], v[26:27] op_sel_hi:[1,0,1]
	v_pk_fma_f32 v[28:29], v[128:129], v[170:171], v[28:29] op_sel_hi:[1,0,1]
	v_pk_fma_f32 v[18:19], v[126:127], v[172:173], v[18:19] op_sel_hi:[1,0,1]
	v_pk_fma_f32 v[20:21], v[128:129], v[172:173], v[20:21] op_sel_hi:[1,0,1]
	v_pk_fma_f32 v[14:15], v[126:127], v[174:175], v[14:15] op_sel_hi:[1,0,1]
	v_pk_fma_f32 v[16:17], v[128:129], v[174:175], v[16:17] op_sel_hi:[1,0,1]
	v_pk_fma_f32 v[10:11], v[126:127], v[176:177], v[10:11] op_sel_hi:[1,0,1]
	v_pk_fma_f32 v[12:13], v[128:129], v[176:177], v[12:13] op_sel_hi:[1,0,1]
	v_pk_fma_f32 v[6:7], v[126:127], v[178:179], v[6:7] op_sel_hi:[1,0,1]
	v_pk_fma_f32 v[8:9], v[128:129], v[178:179], v[8:9] op_sel_hi:[1,0,1]
	v_pk_fma_f32 v[2:3], v[126:127], v[182:183], v[2:3] op_sel_hi:[1,0,1]
	v_pk_fma_f32 v[4:5], v[128:129], v[182:183], v[4:5] op_sel_hi:[1,0,1]
	global_load_dwordx4 v[138:141], v[228:229], off
	global_load_dwordx4 v[126:129], v[224:225], off
	s_cmpk_lg_i32 s17, 0x1e0
	s_cbranch_scc1 .Lpm_loop
	v_add_u32_e32 v232, s17, v1
	s_add_i32 s17, s17, 32
	ds_read_b128 v[58:61], v232
	ds_read_b128 v[62:65], v232 offset:16
	ds_read_b128 v[66:69], v232 offset:8192
	ds_read_b128 v[70:73], v232 offset:8208
	ds_read_b128 v[74:77], v232 offset:16384
	ds_read_b128 v[78:81], v232 offset:16400
	ds_read_b128 v[82:85], v232 offset:24576
	ds_read_b128 v[86:89], v232 offset:24592
	ds_read_b128 v[90:93], v232 offset:32768
	ds_read_b128 v[94:97], v232 offset:32784
	ds_read_b128 v[98:101], v232 offset:40960
	ds_read_b128 v[102:105], v232 offset:40976
	ds_read_b128 v[106:109], v232 offset:49152
	ds_read_b128 v[110:113], v232 offset:49168
	ds_read_b128 v[114:117], v232 offset:57344
	ds_read_b128 v[118:121], v232 offset:57360
	v_add_u32_e32 v48, 0x10000, v232
	v_add_u32_e32 v49, 0x10010, v232
	ds_read_b128 v[142:145], v48
	ds_read_b128 v[146:149], v49
	s_waitcnt lgkmcnt(14)
	v_mov_b32_e32 v48, v61
	v_mov_b32_e32 v150, v69
	s_waitcnt lgkmcnt(13)
	v_mov_b32_e32 v152, v77
	s_waitcnt lgkmcnt(11)
	v_mov_b32_e32 v154, v85
	s_waitcnt lgkmcnt(9)
	v_mov_b32_e32 v156, v93
	s_waitcnt lgkmcnt(7)
	v_mov_b32_e32 v158, v101
	s_waitcnt lgkmcnt(5)
	v_mov_b32_e32 v160, v109
	s_waitcnt lgkmcnt(3)
	v_mov_b32_e32 v162, v117
	s_waitcnt lgkmcnt(1)
	v_mov_b32_e32 v180, v145
	v_mov_b32_e32 v164, v65
	v_mov_b32_e32 v166, v73
	v_mov_b32_e32 v168, v81
	v_mov_b32_e32 v170, v89
	v_mov_b32_e32 v172, v97
	v_mov_b32_e32 v174, v105
	v_mov_b32_e32 v176, v113
	v_mov_b32_e32 v178, v121
	s_waitcnt lgkmcnt(0)
	v_mov_b32_e32 v182, v149
	v_lshl_add_u64 v[42:43], v[42:43], 0, s[12:13]
	s_waitcnt vmcnt(7)
	v_pk_fma_f32 v[22:23], v[58:59], v[50:51], v[22:23] op_sel_hi:[0,1,1]
	v_pk_fma_f32 v[24:25], v[58:59], v[52:53], v[24:25] op_sel_hi:[0,1,1]
	v_pk_fma_f32 v[34:35], v[50:51], v[66:67], v[34:35] op_sel_hi:[1,0,1]
	v_pk_fma_f32 v[36:37], v[52:53], v[66:67], v[36:37] op_sel_hi:[1,0,1]
	v_pk_fma_f32 v[30:31], v[50:51], v[74:75], v[30:31] op_sel_hi:[1,0,1]
	v_pk_fma_f32 v[32:33], v[52:53], v[74:75], v[32:33] op_sel_hi:[1,0,1]
	v_pk_fma_f32 v[26:27], v[50:51], v[82:83], v[26:27] op_sel_hi:[1,0,1]
	v_pk_fma_f32 v[28:29], v[52:53], v[82:83], v[28:29] op_sel_hi:[1,0,1]
	v_pk_fma_f32 v[18:19], v[50:51], v[90:91], v[18:19] op_sel_hi:[1,0,1]
	v_pk_fma_f32 v[20:21], v[52:53], v[90:91], v[20:21] op_sel_hi:[1,0,1]
	v_pk_fma_f32 v[14:15], v[50:51], v[98:99], v[14:15] op_sel_hi:[1,0,1]
	v_pk_fma_f32 v[16:17], v[52:53], v[98:99], v[16:17] op_sel_hi:[1,0,1]
	v_pk_fma_f32 v[10:11], v[50:51], v[106:107], v[10:11] op_sel_hi:[1,0,1]
	v_pk_fma_f32 v[12:13], v[52:53], v[106:107], v[12:13] op_sel_hi:[1,0,1]
	v_pk_fma_f32 v[6:7], v[50:51], v[114:115], v[6:7] op_sel_hi:[1,0,1]
	v_pk_fma_f32 v[8:9], v[52:53], v[114:115], v[8:9] op_sel_hi:[1,0,1]
	v_pk_fma_f32 v[2:3], v[50:51], v[142:143], v[2:3] op_sel_hi:[1,0,1]
	v_pk_fma_f32 v[4:5], v[52:53], v[142:143], v[4:5] op_sel_hi:[1,0,1]
	s_waitcnt vmcnt(6)
	v_pk_fma_f32 v[22:23], v[58:59], v[54:55], v[22:23] op_sel:[1,0,0]
	v_pk_fma_f32 v[24:25], v[58:59], v[56:57], v[24:25] op_sel:[1,0,0]
	v_pk_fma_f32 v[34:35], v[54:55], v[66:67], v[34:35] op_sel:[0,1,0]
	v_pk_fma_f32 v[36:37], v[56:57], v[66:67], v[36:37] op_sel:[0,1,0]
	v_pk_fma_f32 v[30:31], v[54:55], v[74:75], v[30:31] op_sel:[0,1,0]
	v_pk_fma_f32 v[32:33], v[56:57], v[74:75], v[32:33] op_sel:[0,1,0]
	v_pk_fma_f32 v[26:27], v[54:55], v[82:83], v[26:27] op_sel:[0,1,0]
	v_pk_fma_f32 v[28:29], v[56:57], v[82:83], v[28:29] op_sel:[0,1,0]
	v_pk_fma_f32 v[18:19], v[54:55], v[90:91], v[18:19] op_sel:[0,1,0]
	v_pk_fma_f32 v[20:21], v[56:57], v[90:91], v[20:21] op_sel:[0,1,0]
	v_pk_fma_f32 v[14:15], v[54:55], v[98:99], v[14:15] op_sel:[0,1,0]
	v_pk_fma_f32 v[16:17], v[56:57], v[98:99], v[16:17] op_sel:[0,1,0]
	v_pk_fma_f32 v[10:11], v[54:55], v[106:107], v[10:11] op_sel:[0,1,0]
	v_pk_fma_f32 v[12:13], v[56:57], v[106:107], v[12:13] op_sel:[0,1,0]
	v_pk_fma_f32 v[6:7], v[54:55], v[114:115], v[6:7] op_sel:[0,1,0]
	v_pk_fma_f32 v[8:9], v[56:57], v[114:115], v[8:9] op_sel:[0,1,0]
	v_pk_fma_f32 v[2:3], v[54:55], v[142:143], v[2:3] op_sel:[0,1,0]
	v_pk_fma_f32 v[4:5], v[56:57], v[142:143], v[4:5] op_sel:[0,1,0]
	s_waitcnt vmcnt(5)
	v_pk_fma_f32 v[22:23], v[60:61], v[44:45], v[22:23] op_sel_hi:[0,1,1]
	v_pk_fma_f32 v[24:25], v[60:61], v[46:47], v[24:25] op_sel_hi:[0,1,1]
	v_pk_fma_f32 v[34:35], v[44:45], v[68:69], v[34:35] op_sel_hi:[1,0,1]
	v_pk_fma_f32 v[36:37], v[46:47], v[68:69], v[36:37] op_sel_hi:[1,0,1]
	v_pk_fma_f32 v[30:31], v[44:45], v[76:77], v[30:31] op_sel_hi:[1,0,1]
	v_pk_fma_f32 v[32:33], v[46:47], v[76:77], v[32:33] op_sel_hi:[1,0,1]
	v_pk_fma_f32 v[26:27], v[44:45], v[84:85], v[26:27] op_sel_hi:[1,0,1]
	v_pk_fma_f32 v[28:29], v[46:47], v[84:85], v[28:29] op_sel_hi:[1,0,1]
	v_pk_fma_f32 v[18:19], v[44:45], v[92:93], v[18:19] op_sel_hi:[1,0,1]
	v_pk_fma_f32 v[20:21], v[46:47], v[92:93], v[20:21] op_sel_hi:[1,0,1]
	v_pk_fma_f32 v[14:15], v[44:45], v[100:101], v[14:15] op_sel_hi:[1,0,1]
	v_pk_fma_f32 v[16:17], v[46:47], v[100:101], v[16:17] op_sel_hi:[1,0,1]
	v_pk_fma_f32 v[10:11], v[44:45], v[108:109], v[10:11] op_sel_hi:[1,0,1]
	v_pk_fma_f32 v[12:13], v[46:47], v[108:109], v[12:13] op_sel_hi:[1,0,1]
	v_pk_fma_f32 v[6:7], v[44:45], v[116:117], v[6:7] op_sel_hi:[1,0,1]
	v_pk_fma_f32 v[8:9], v[46:47], v[116:117], v[8:9] op_sel_hi:[1,0,1]
	v_pk_fma_f32 v[2:3], v[44:45], v[144:145], v[2:3] op_sel_hi:[1,0,1]
	v_pk_fma_f32 v[4:5], v[46:47], v[144:145], v[4:5] op_sel_hi:[1,0,1]
	s_waitcnt vmcnt(4)
	v_pk_fma_f32 v[22:23], v[48:49], v[122:123], v[22:23] op_sel_hi:[0,1,1]
	v_pk_fma_f32 v[24:25], v[48:49], v[124:125], v[24:25] op_sel_hi:[0,1,1]
	v_pk_fma_f32 v[34:35], v[122:123], v[150:151], v[34:35] op_sel_hi:[1,0,1]
	v_pk_fma_f32 v[36:37], v[124:125], v[150:151], v[36:37] op_sel_hi:[1,0,1]
	v_pk_fma_f32 v[30:31], v[122:123], v[152:153], v[30:31] op_sel_hi:[1,0,1]
	v_pk_fma_f32 v[32:33], v[124:125], v[152:153], v[32:33] op_sel_hi:[1,0,1]
	v_pk_fma_f32 v[26:27], v[122:123], v[154:155], v[26:27] op_sel_hi:[1,0,1]
	v_pk_fma_f32 v[28:29], v[124:125], v[154:155], v[28:29] op_sel_hi:[1,0,1]
	v_pk_fma_f32 v[18:19], v[122:123], v[156:157], v[18:19] op_sel_hi:[1,0,1]
	v_pk_fma_f32 v[20:21], v[124:125], v[156:157], v[20:21] op_sel_hi:[1,0,1]
	v_pk_fma_f32 v[14:15], v[122:123], v[158:159], v[14:15] op_sel_hi:[1,0,1]
	v_pk_fma_f32 v[16:17], v[124:125], v[158:159], v[16:17] op_sel_hi:[1,0,1]
	v_pk_fma_f32 v[10:11], v[122:123], v[160:161], v[10:11] op_sel_hi:[1,0,1]
	v_pk_fma_f32 v[12:13], v[124:125], v[160:161], v[12:13] op_sel_hi:[1,0,1]
	v_pk_fma_f32 v[6:7], v[122:123], v[162:163], v[6:7] op_sel_hi:[1,0,1]
	v_pk_fma_f32 v[8:9], v[124:125], v[162:163], v[8:9] op_sel_hi:[1,0,1]
	v_pk_fma_f32 v[2:3], v[122:123], v[180:181], v[2:3] op_sel_hi:[1,0,1]
	v_pk_fma_f32 v[4:5], v[124:125], v[180:181], v[4:5] op_sel_hi:[1,0,1]
	s_waitcnt vmcnt(3)
	v_pk_fma_f32 v[22:23], v[62:63], v[130:131], v[22:23] op_sel_hi:[0,1,1]
	v_pk_fma_f32 v[24:25], v[62:63], v[132:133], v[24:25] op_sel_hi:[0,1,1]
	v_pk_fma_f32 v[34:35], v[130:131], v[70:71], v[34:35] op_sel_hi:[1,0,1]
	v_pk_fma_f32 v[36:37], v[132:133], v[70:71], v[36:37] op_sel_hi:[1,0,1]
	v_pk_fma_f32 v[30:31], v[130:131], v[78:79], v[30:31] op_sel_hi:[1,0,1]
	v_pk_fma_f32 v[32:33], v[132:133], v[78:79], v[32:33] op_sel_hi:[1,0,1]
	v_pk_fma_f32 v[26:27], v[130:131], v[86:87], v[26:27] op_sel_hi:[1,0,1]
	v_pk_fma_f32 v[28:29], v[132:133], v[86:87], v[28:29] op_sel_hi:[1,0,1]
	v_pk_fma_f32 v[18:19], v[130:131], v[94:95], v[18:19] op_sel_hi:[1,0,1]
	v_pk_fma_f32 v[20:21], v[132:133], v[94:95], v[20:21] op_sel_hi:[1,0,1]
	v_pk_fma_f32 v[14:15], v[130:131], v[102:103], v[14:15] op_sel_hi:[1,0,1]
	v_pk_fma_f32 v[16:17], v[132:133], v[102:103], v[16:17] op_sel_hi:[1,0,1]
	v_pk_fma_f32 v[10:11], v[130:131], v[110:111], v[10:11] op_sel_hi:[1,0,1]
	v_pk_fma_f32 v[12:13], v[132:133], v[110:111], v[12:13] op_sel_hi:[1,0,1]
	v_pk_fma_f32 v[6:7], v[130:131], v[118:119], v[6:7] op_sel_hi:[1,0,1]
	v_pk_fma_f32 v[8:9], v[132:133], v[118:119], v[8:9] op_sel_hi:[1,0,1]
	v_pk_fma_f32 v[2:3], v[130:131], v[146:147], v[2:3] op_sel_hi:[1,0,1]
	v_pk_fma_f32 v[4:5], v[132:133], v[146:147], v[4:5] op_sel_hi:[1,0,1]
	s_waitcnt vmcnt(2)
	v_pk_fma_f32 v[22:23], v[62:63], v[134:135], v[22:23] op_sel:[1,0,0]
	v_pk_fma_f32 v[24:25], v[62:63], v[136:137], v[24:25] op_sel:[1,0,0]
	v_pk_fma_f32 v[34:35], v[134:135], v[70:71], v[34:35] op_sel:[0,1,0]
	v_pk_fma_f32 v[36:37], v[136:137], v[70:71], v[36:37] op_sel:[0,1,0]
	v_pk_fma_f32 v[30:31], v[134:135], v[78:79], v[30:31] op_sel:[0,1,0]
	v_pk_fma_f32 v[32:33], v[136:137], v[78:79], v[32:33] op_sel:[0,1,0]
	v_pk_fma_f32 v[26:27], v[134:135], v[86:87], v[26:27] op_sel:[0,1,0]
	v_pk_fma_f32 v[28:29], v[136:137], v[86:87], v[28:29] op_sel:[0,1,0]
	v_pk_fma_f32 v[18:19], v[134:135], v[94:95], v[18:19] op_sel:[0,1,0]
	v_pk_fma_f32 v[20:21], v[136:137], v[94:95], v[20:21] op_sel:[0,1,0]
	v_pk_fma_f32 v[14:15], v[134:135], v[102:103], v[14:15] op_sel:[0,1,0]
	v_pk_fma_f32 v[16:17], v[136:137], v[102:103], v[16:17] op_sel:[0,1,0]
	v_pk_fma_f32 v[10:11], v[134:135], v[110:111], v[10:11] op_sel:[0,1,0]
	v_pk_fma_f32 v[12:13], v[136:137], v[110:111], v[12:13] op_sel:[0,1,0]
	v_pk_fma_f32 v[6:7], v[134:135], v[118:119], v[6:7] op_sel:[0,1,0]
	v_pk_fma_f32 v[8:9], v[136:137], v[118:119], v[8:9] op_sel:[0,1,0]
	v_pk_fma_f32 v[2:3], v[134:135], v[146:147], v[2:3] op_sel:[0,1,0]
	v_pk_fma_f32 v[4:5], v[136:137], v[146:147], v[4:5] op_sel:[0,1,0]
	s_waitcnt vmcnt(0)
	v_pk_fma_f32 v[22:23], v[64:65], v[138:139], v[22:23] op_sel_hi:[0,1,1]
	v_pk_fma_f32 v[24:25], v[64:65], v[140:141], v[24:25] op_sel_hi:[0,1,1]
	v_pk_fma_f32 v[34:35], v[138:139], v[72:73], v[34:35] op_sel_hi:[1,0,1]
	v_pk_fma_f32 v[36:37], v[140:141], v[72:73], v[36:37] op_sel_hi:[1,0,1]
	v_pk_fma_f32 v[30:31], v[138:139], v[80:81], v[30:31] op_sel_hi:[1,0,1]
	v_pk_fma_f32 v[32:33], v[140:141], v[80:81], v[32:33] op_sel_hi:[1,0,1]
	v_pk_fma_f32 v[26:27], v[138:139], v[88:89], v[26:27] op_sel_hi:[1,0,1]
	v_pk_fma_f32 v[28:29], v[140:141], v[88:89], v[28:29] op_sel_hi:[1,0,1]
	v_pk_fma_f32 v[18:19], v[138:139], v[96:97], v[18:19] op_sel_hi:[1,0,1]
	v_pk_fma_f32 v[20:21], v[140:141], v[96:97], v[20:21] op_sel_hi:[1,0,1]
	v_pk_fma_f32 v[14:15], v[138:139], v[104:105], v[14:15] op_sel_hi:[1,0,1]
	v_pk_fma_f32 v[16:17], v[140:141], v[104:105], v[16:17] op_sel_hi:[1,0,1]
	v_pk_fma_f32 v[10:11], v[138:139], v[112:113], v[10:11] op_sel_hi:[1,0,1]
	v_pk_fma_f32 v[12:13], v[140:141], v[112:113], v[12:13] op_sel_hi:[1,0,1]
	v_pk_fma_f32 v[6:7], v[138:139], v[120:121], v[6:7] op_sel_hi:[1,0,1]
	v_pk_fma_f32 v[8:9], v[140:141], v[120:121], v[8:9] op_sel_hi:[1,0,1]
	v_pk_fma_f32 v[2:3], v[138:139], v[148:149], v[2:3] op_sel_hi:[1,0,1]
	v_pk_fma_f32 v[4:5], v[140:141], v[148:149], v[4:5] op_sel_hi:[1,0,1]
	v_pk_fma_f32 v[22:23], v[164:165], v[126:127], v[22:23] op_sel_hi:[0,1,1]
	v_pk_fma_f32 v[24:25], v[164:165], v[128:129], v[24:25] op_sel_hi:[0,1,1]
	v_pk_fma_f32 v[34:35], v[126:127], v[166:167], v[34:35] op_sel_hi:[1,0,1]
	v_pk_fma_f32 v[36:37], v[128:129], v[166:167], v[36:37] op_sel_hi:[1,0,1]
	v_pk_fma_f32 v[30:31], v[126:127], v[168:169], v[30:31] op_sel_hi:[1,0,1]
	v_pk_fma_f32 v[32:33], v[128:129], v[168:169], v[32:33] op_sel_hi:[1,0,1]
	v_pk_fma_f32 v[26:27], v[126:127], v[170:171], v[26:27] op_sel_hi:[1,0,1]
	v_pk_fma_f32 v[28:29], v[128:129], v[170:171], v[28:29] op_sel_hi:[1,0,1]
	v_pk_fma_f32 v[18:19], v[126:127], v[172:173], v[18:19] op_sel_hi:[1,0,1]
	v_pk_fma_f32 v[20:21], v[128:129], v[172:173], v[20:21] op_sel_hi:[1,0,1]
	v_pk_fma_f32 v[14:15], v[126:127], v[174:175], v[14:15] op_sel_hi:[1,0,1]
	v_pk_fma_f32 v[16:17], v[128:129], v[174:175], v[16:17] op_sel_hi:[1,0,1]
	v_pk_fma_f32 v[10:11], v[126:127], v[176:177], v[10:11] op_sel_hi:[1,0,1]
	v_pk_fma_f32 v[12:13], v[128:129], v[176:177], v[12:13] op_sel_hi:[1,0,1]
	v_pk_fma_f32 v[6:7], v[126:127], v[178:179], v[6:7] op_sel_hi:[1,0,1]
	v_pk_fma_f32 v[8:9], v[128:129], v[178:179], v[8:9] op_sel_hi:[1,0,1]
	v_pk_fma_f32 v[2:3], v[126:127], v[182:183], v[2:3] op_sel_hi:[1,0,1]
	v_pk_fma_f32 v[4:5], v[128:129], v[182:183], v[4:5] op_sel_hi:[1,0,1]
	ds_write_b128 v39, v[22:25]
	ds_write_b128 v39, v[34:37] offset:16
	ds_write_b128 v39, v[30:33] offset:32
	ds_write_b128 v39, v[26:29] offset:48
	ds_write_b128 v39, v[18:21] offset:64
	ds_write_b128 v39, v[14:17] offset:80
	ds_write_b128 v39, v[10:13] offset:96
	ds_write_b128 v39, v[6:9] offset:112
	ds_write_b128 v39, v[2:5] offset:128
